# v46 + MLA half 1: first four V-fragment reads of P.V issued three QK pairs early into dead v[206:213]; P.V waits recomputed
# baseline (speedup 1.0000x reference)
.LBB0_543:
	s_mov_b32 s23, s17
	s_mov_b32 s17, s0
	s_add_i32 s71, 0, 0x10000
	ds_read_b128 v[66:69], v174 offset:49152
	ds_read_b128 v[70:73], v174 offset:57344
	ds_read_b128 v[206:209], v176 offset:49152
	ds_read_b128 v[210:213], v176 offset:57344
	v_fma_f32 v152, v74, s34, v146
	v_fma_f32 v153, v75, s34, v146
	v_fma_f32 v150, v76, s34, v146
	v_fma_f32 v151, v77, s34, v146
	v_fma_f32 v148, v78, s34, v146
	v_fma_f32 v149, v79, s34, v146
	v_fma_f32 v147, v81, s34, v146
	v_fma_f32 v146, v80, s34, v146
	v_exp_f32_e32 v229, v229
	v_exp_f32_e32 v231, v231
	v_exp_f32_e32 v227, v227
	v_exp_f32_e32 v230, v230
	v_exp_f32_e32 v226, v226
	v_exp_f32_e32 v228, v228
	s_waitcnt lgkmcnt(0)
	v_mfma_f32_32x32x16_bf16 v[82:97], v[66:69], v[142:145], 0
	s_add_i32 s0, 0, 0x16000
	v_exp_f32_e32 v240, v146
	v_add_f32_e32 v146, 0, v229
	v_add_f32_e32 v146, v231, v146
	v_add_f32_e32 v146, v227, v146
	v_add_f32_e32 v146, v230, v146
	v_add_f32_e32 v146, v226, v146
	v_exp_f32_e32 v224, v224
	v_exp_f32_e32 v225, v225
	v_exp_f32_e32 v221, v221
	v_exp_f32_e32 v223, v223
	v_mfma_f32_32x32x16_bf16 v[66:81], v[70:73], v[142:145], 0
	v_exp_f32_e32 v220, v220
	v_exp_f32_e32 v222, v222
	v_add_f32_e32 v146, v228, v146
	v_add_f32_e32 v146, v224, v146
	v_add_f32_e32 v146, v225, v146
	v_add_f32_e32 v146, v221, v146
	v_add_f32_e32 v146, v223, v146
	v_add_f32_e32 v146, v220, v146
	v_add_f32_e32 v146, v222, v146
	v_exp_f32_e32 v217, v217
	v_exp_f32_e32 v219, v219
	v_exp_f32_e32 v216, v216
	v_exp_f32_e32 v218, v218
	v_mfma_f32_32x32x16_bf16 v[82:97], v[206:209], v[138:141], v[82:97]
	v_exp_f32_e32 v164, v164
	v_add_f32_e32 v146, v217, v146
	v_exp_f32_e32 v165, v165
	v_add_f32_e32 v146, v219, v146
	v_exp_f32_e32 v197, v162
	v_add_f32_e32 v146, v216, v146
	v_add_f32_e32 v146, v218, v146
	v_mfma_f32_32x32x16_bf16 v[66:81], v[210:213], v[138:141], v[66:81]
	ds_read_b128 v[206:209], v178 offset:49152
	ds_read_b128 v[210:213], v178 offset:57344
	s_add_u32 s4, s38, s20
	s_addc_u32 s5, s39, s21
	s_add_u32 s24, s4, 0x149ec400
	s_addc_u32 s25, s5, 0
	s_mov_b32 m0, s90
	v_lshl_add_u64 v[254:255], v[246:247], 0, s[24:25]
	s_lshl_b32 s18, s22, 14
	global_load_lds_dwordx4 v[254:255], off
	s_add_u32 s24, s4, 0x14a0c400
	s_addc_u32 s25, s5, 0
	s_mov_b32 m0, s91
	v_lshl_add_u64 v[254:255], v[246:247], 0, s[24:25]
	s_add_i32 s1, s89, s18
	global_load_lds_dwordx4 v[254:255], off
	s_add_u32 s24, s4, 0x149ec500
	s_addc_u32 s25, s5, 0
	s_mov_b32 m0, s1
	v_lshl_add_u64 v[254:255], v[248:249], 0, s[24:25]
	global_load_lds_dwordx4 v[254:255], off
	s_add_u32 s24, s4, 0x14a0c500
	s_addc_u32 s25, s5, 0
	s_add_i32 m0, s1, 0x2000
	v_lshl_add_u64 v[254:255], v[248:249], 0, s[24:25]
	global_load_lds_dwordx4 v[254:255], off
	s_add_u32 s4, s38, s88
	s_addc_u32 s5, s39, s87
	s_add_u32 s4, s4, s36
	s_addc_u32 s5, s5, s37
	s_mov_b32 m0, s92
	v_lshl_add_u64 v[254:255], v[250:251], 0, s[4:5]
	global_load_lds_dwordx4 v[254:255], off
	v_exp_f32_e32 v156, v156
	v_add_f32_e32 v146, v164, v146
	v_exp_f32_e32 v157, v157
	v_add_f32_e32 v146, v165, v146
	v_add_f32_e32 v146, v197, v146
	v_exp_f32_e32 v241, v147
	s_waitcnt lgkmcnt(0)
	v_mfma_f32_32x32x16_bf16 v[82:97], v[206:209], v[134:137], v[82:97]
	v_mfma_f32_32x32x16_bf16 v[66:81], v[210:213], v[134:137], v[66:81]
	ds_read_b128 v[208:211], v180 offset:49152
	ds_read_b128 v[212:215], v180 offset:57344
	s_waitcnt lgkmcnt(0)
	v_mfma_f32_32x32x16_bf16 v[82:97], v[208:211], v[130:133], v[82:97]
	v_mfma_f32_32x32x16_bf16 v[66:81], v[212:215], v[130:133], v[66:81]
	ds_read_b128 v[208:211], v182 offset:49152
	ds_read_b128 v[212:215], v182 offset:57344
	s_waitcnt lgkmcnt(0)
	v_mfma_f32_32x32x16_bf16 v[82:97], v[208:211], v[126:129], v[82:97]
	v_mfma_f32_32x32x16_bf16 v[66:81], v[212:215], v[126:129], v[66:81]
	ds_read_b128 v[210:213], v186 offset:49152
	ds_read_b128 v[232:235], v186 offset:57344
	s_waitcnt lgkmcnt(0)
	v_mfma_f32_32x32x16_bf16 v[82:97], v[210:213], v[122:125], v[82:97]
	v_mfma_f32_32x32x16_bf16 v[66:81], v[232:235], v[122:125], v[66:81]
	ds_read_b128 v[210:213], v188 offset:49152
	ds_read_b128 v[232:235], v188 offset:57344
	s_waitcnt lgkmcnt(0)
	v_mfma_f32_32x32x16_bf16 v[82:97], v[210:213], v[118:121], v[82:97]
	v_mfma_f32_32x32x16_bf16 v[66:81], v[232:235], v[118:121], v[66:81]
	ds_read_b128 v[212:215], v190 offset:49152
	ds_read_b128 v[232:235], v190 offset:57344
	s_waitcnt lgkmcnt(0)
	v_mfma_f32_32x32x16_bf16 v[82:97], v[212:215], v[114:117], v[82:97]
	v_mfma_f32_32x32x16_bf16 v[66:81], v[232:235], v[114:117], v[66:81]
	ds_read_b128 v[212:215], v192 offset:8192
	ds_read_b128 v[232:235], v192 offset:12288
	s_waitcnt lgkmcnt(0)
	v_mfma_f32_32x32x16_bf16 v[82:97], v[212:215], v[110:113], v[82:97]
	v_exp_f32_e32 v215, v163
	s_nop 0
	v_add_f32_e32 v146, v215, v146
	v_mfma_f32_32x32x16_bf16 v[66:81], v[232:235], v[110:113], v[66:81]
	s_lshl_b32 s24, s17, 14
	v_add_u32_e32 v245, s24, v200
	ds_read_b64_tr_b16 v[206:207], v245 offset:0
	ds_read_b64_tr_b16 v[208:209], v245 offset:0x800
	ds_read_b64_tr_b16 v[210:211], v245 offset:0x1000
	ds_read_b64_tr_b16 v[212:213], v245 offset:0x1800
	ds_read_b128 v[232:235], v194 offset:8192
	ds_read_b128 v[236:239], v194 offset:12288
	v_add_f32_e32 v146, v156, v146
	v_add_f32_e32 v146, v157, v146
	s_waitcnt lgkmcnt(0)
	v_mfma_f32_32x32x16_bf16 v[82:97], v[232:235], v[106:109], v[82:97]
	v_mfma_f32_32x32x16_bf16 v[66:81], v[236:239], v[106:109], v[66:81]
	ds_read_b128 v[232:235], v196 offset:8192
	ds_read_b128 v[236:239], v196 offset:12288
	s_waitcnt lgkmcnt(0)
	v_mfma_f32_32x32x16_bf16 v[82:97], v[232:235], v[102:105], v[82:97]
	v_mfma_f32_32x32x16_bf16 v[66:81], v[236:239], v[102:105], v[66:81]
	ds_read_b128 v[232:235], v199 offset:8192
	ds_read_b128 v[236:239], v199 offset:12288
	s_waitcnt lgkmcnt(0)
	v_mfma_f32_32x32x16_bf16 v[82:97], v[232:235], v[98:101], v[82:97]
	v_exp_f32_e32 v232, v154
	v_exp_f32_e32 v233, v155
	v_exp_f32_e32 v234, v152
	v_exp_f32_e32 v235, v153
	v_add_f32_e32 v146, v232, v146
	v_add_f32_e32 v146, v233, v146
	v_add_f32_e32 v146, v234, v146
	v_mfma_f32_32x32x16_bf16 v[66:81], v[236:239], v[98:101], v[66:81]
	v_exp_f32_e32 v236, v150
	v_exp_f32_e32 v237, v151
	v_exp_f32_e32 v238, v148
	v_exp_f32_e32 v239, v149
	v_add_f32_e32 v146, v235, v146
	v_add_f32_e32 v146, v236, v146
	v_add_f32_e32 v146, v237, v146
	v_add_f32_e32 v146, v238, v146
	v_add_f32_e32 v146, v239, v146
	v_add_f32_e32 v146, v240, v146
	v_add_f32_e32 v162, v241, v146
	v_mov_b32_e32 v163, v162
	s_nop 1
	v_permlane32_swap_b32_e32 v162, v163
	v_cvt_pk_bf16_f32 v146, v229, v231
	v_cvt_pk_bf16_f32 v147, v227, v230
	v_cvt_pk_bf16_f32 v148, v226, v228
	v_cvt_pk_bf16_f32 v149, v224, v225
	v_cvt_pk_bf16_f32 v150, v221, v223
	v_cvt_pk_bf16_f32 v151, v220, v222
	v_cvt_pk_bf16_f32 v152, v217, v219
	v_cvt_pk_bf16_f32 v153, v216, v218
	v_cvt_pk_bf16_f32 v154, v164, v165
	v_cvt_pk_bf16_f32 v155, v197, v215
	v_cvt_pk_bf16_f32 v156, v156, v157
	v_cvt_pk_bf16_f32 v157, v232, v233
	v_cvt_pk_bf16_f32 v216, v234, v235
	v_cvt_pk_bf16_f32 v217, v236, v237
	v_cvt_pk_bf16_f32 v218, v238, v239
	v_cvt_pk_bf16_f32 v219, v240, v241
	s_nop 0
	v_permlane32_swap_b32_e32 v146, v148
	v_permlane32_swap_b32_e32 v147, v149
	v_permlane32_swap_b32_e32 v150, v152
	v_permlane32_swap_b32_e32 v151, v153
	v_permlane32_swap_b32_e32 v154, v156
	v_permlane32_swap_b32_e32 v155, v157
	v_permlane32_swap_b32_e32 v216, v218
	v_permlane32_swap_b32_e32 v217, v219
	s_lshl_b32 s24, s17, 14
	v_add_u32_e32 v197, s24, v200
	ds_read_b64_tr_b16 v[228:229], v197 offset:0x2000
	ds_read_b64_tr_b16 v[230:231], v197 offset:0x2800
	ds_read_b64_tr_b16 v[232:233], v197 offset:0x3000
	ds_read_b64_tr_b16 v[234:235], v197 offset:0x3800
	s_nop 0
	v_mfma_f32_32x32x16_bf16 v[2:17], v[146:149], v[206:209], v[2:17]
	ds_read_b64_tr_b16 v[220:221], v197 offset:0x200
	ds_read_b64_tr_b16 v[222:223], v197 offset:0xa00
	v_max_f32_e32 v164, v83, v83
	v_max_f32_e32 v165, v82, v82
	v_max_f32_e32 v164, v165, v164
	v_max3_f32 v164, v164, v84, v85
	v_max3_f32 v164, v164, v86, v87
	v_mfma_f32_32x32x16_bf16 v[2:17], v[150:153], v[210:213], v[2:17]
	ds_read_b64_tr_b16 v[224:225], v197 offset:0x1200
	ds_read_b64_tr_b16 v[226:227], v197 offset:0x1a00
	v_max3_f32 v164, v164, v88, v89
	v_max3_f32 v164, v164, v90, v91
	v_max3_f32 v164, v164, v92, v93
	v_max3_f32 v164, v164, v94, v95
	v_max3_f32 v164, v164, v96, v97
	s_waitcnt lgkmcnt(6)
	v_mfma_f32_32x32x16_bf16 v[2:17], v[154:157], v[228:231], v[2:17]
	ds_read_b64_tr_b16 v[228:229], v197 offset:0x2200
	ds_read_b64_tr_b16 v[230:231], v197 offset:0x2a00
	ds_read_b64_tr_b16 v[236:237], v197 offset:0x3200
	ds_read_b64_tr_b16 v[238:239], v197 offset:0x3a00
	s_waitcnt lgkmcnt(8)
	v_mfma_f32_32x32x16_bf16 v[2:17], v[216:219], v[232:235], v[2:17]
	s_waitcnt lgkmcnt(6)
	v_mfma_f32_32x32x16_bf16 v[50:65], v[146:149], v[220:223], v[50:65]
	v_max3_f32 v164, v164, v66, v67
	v_max3_f32 v164, v164, v68, v69
	v_max3_f32 v164, v164, v70, v71
	v_max3_f32 v164, v164, v72, v73
	v_max3_f32 v164, v164, v74, v75
	v_max3_f32 v164, v164, v76, v77
	v_max3_f32 v164, v164, v78, v79
	s_waitcnt lgkmcnt(4)
	v_mfma_f32_32x32x16_bf16 v[50:65], v[150:153], v[224:227], v[50:65]
	v_max3_f32 v164, v164, v80, v81
	v_mov_b32_e32 v165, v164
	s_nop 1
	v_permlane32_swap_b32_e32 v164, v165
	ds_read_b64_tr_b16 v[220:221], v197 offset:0x400
	v_max_f32_e32 v165, v165, v165
	v_max_f32_e32 v164, v164, v164
	s_waitcnt lgkmcnt(3)
	v_mfma_f32_32x32x16_bf16 v[50:65], v[154:157], v[228:231], v[50:65]
	ds_read_b64_tr_b16 v[222:223], v197 offset:0xc00
	v_max_f32_e32 v164, v164, v165
	v_max_f32_e32 v165, v202, v202
	ds_read_b64_tr_b16 v[224:225], v197 offset:0x1400
	v_max_f32_e32 v165, v165, v164
	ds_read_b64_tr_b16 v[226:227], v197 offset:0x1c00
	v_sub_f32_e32 v215, v164, v202
	s_waitcnt lgkmcnt(4)
	v_mfma_f32_32x32x16_bf16 v[50:65], v[216:219], v[236:239], v[50:65]
	v_sub_f32_e32 v164, v202, v165
	ds_read_b64_tr_b16 v[228:229], v197 offset:0x2400
	v_mul_f32_e32 v164, 0x3dd53b94, v164
	ds_read_b64_tr_b16 v[230:231], v197 offset:0x2c00
	v_exp_f32_e32 v164, v164
	ds_read_b64_tr_b16 v[232:233], v197 offset:0x3400
	v_cmp_ge_f32_e32 vcc, s77, v215
	ds_read_b64_tr_b16 v[234:235], v197 offset:0x3c00
	s_cmp_eq_u64 vcc, exec
	s_cselect_b64 s[4:5], -1, 0
	v_cndmask_b32_e64 v164, v164, 1.0, s[4:5]
	s_waitcnt lgkmcnt(6)
	v_mfma_f32_32x32x16_bf16 v[34:49], v[146:149], v[220:223], v[34:49]
	ds_read_b64_tr_b16 v[220:221], v197 offset:0x600
	ds_read_b64_tr_b16 v[222:223], v197 offset:0xe00
	s_waitcnt lgkmcnt(6)
	v_mfma_f32_32x32x16_bf16 v[34:49], v[150:153], v[224:227], v[34:49]
	ds_read_b64_tr_b16 v[224:225], v197 offset:0x1600
	ds_read_b64_tr_b16 v[226:227], v197 offset:0x1e00
	s_waitcnt lgkmcnt(6)
	v_mfma_f32_32x32x16_bf16 v[34:49], v[154:157], v[228:231], v[34:49]
	ds_read_b64_tr_b16 v[228:229], v197 offset:0x2600
	ds_read_b64_tr_b16 v[230:231], v197 offset:0x2e00
	ds_read_b64_tr_b16 v[236:237], v197 offset:0x3600
	ds_read_b64_tr_b16 v[238:239], v197 offset:0x3e00
	s_waitcnt lgkmcnt(8)
	v_mfma_f32_32x32x16_bf16 v[34:49], v[216:219], v[232:235], v[34:49]
	s_waitcnt lgkmcnt(6)
	v_mfma_f32_32x32x16_bf16 v[18:33], v[146:149], v[220:223], v[18:33]
	v_cmp_gt_f32_e32 vcc, 1.0, v164
	s_waitcnt lgkmcnt(4)
	v_mfma_f32_32x32x16_bf16 v[18:33], v[150:153], v[224:227], v[18:33]
	s_waitcnt lgkmcnt(2)
	v_mfma_f32_32x32x16_bf16 v[18:33], v[154:157], v[228:231], v[18:33]
	s_waitcnt lgkmcnt(0)
	v_mfma_f32_32x32x16_bf16 v[18:33], v[216:219], v[236:239], v[18:33]
	s_cbranch_vccz .LBB0_547
	s_and_saveexec_b64 s[0:1], s[2:3]
	ds_write_b32 v170, v164 offset:128
	s_or_b64 exec, exec, s[0:1]
	s_waitcnt lgkmcnt(0)
	ds_read_b128 v[146:149], v158 offset:224
	ds_read_b128 v[150:153], v158 offset:192
	ds_read_b128 v[154:157], v158 offset:160
	ds_read_b128 v[216:219], v158 offset:128
	s_waitcnt lgkmcnt(0)
	v_pk_mul_f32 v[16:17], v[16:17], v[148:149]
	v_pk_mul_f32 v[12:13], v[12:13], v[152:153]
	v_pk_mul_f32 v[8:9], v[8:9], v[156:157]
	v_pk_mul_f32 v[4:5], v[4:5], v[218:219]
	v_pk_mul_f32 v[14:15], v[14:15], v[146:147]
	v_pk_mul_f32 v[10:11], v[10:11], v[150:151]
	v_pk_mul_f32 v[6:7], v[6:7], v[154:155]
	v_pk_mul_f32 v[2:3], v[2:3], v[216:217]
	v_pk_mul_f32 v[64:65], v[64:65], v[148:149]
	v_pk_mul_f32 v[60:61], v[60:61], v[152:153]
	v_pk_mul_f32 v[56:57], v[56:57], v[156:157]
	v_pk_mul_f32 v[52:53], v[52:53], v[218:219]
	v_pk_mul_f32 v[62:63], v[62:63], v[146:147]
	v_pk_mul_f32 v[58:59], v[58:59], v[150:151]
	v_pk_mul_f32 v[54:55], v[54:55], v[154:155]
	v_pk_mul_f32 v[50:51], v[50:51], v[216:217]
	v_pk_mul_f32 v[48:49], v[48:49], v[148:149]
	v_pk_mul_f32 v[44:45], v[44:45], v[152:153]
	v_pk_mul_f32 v[40:41], v[40:41], v[156:157]
	v_pk_mul_f32 v[36:37], v[36:37], v[218:219]
	v_pk_mul_f32 v[46:47], v[46:47], v[146:147]
	v_pk_mul_f32 v[42:43], v[42:43], v[150:151]
	v_pk_mul_f32 v[38:39], v[38:39], v[154:155]
	v_pk_mul_f32 v[34:35], v[34:35], v[216:217]
	v_pk_mul_f32 v[32:33], v[32:33], v[148:149]
	v_pk_mul_f32 v[28:29], v[28:29], v[152:153]
	v_pk_mul_f32 v[24:25], v[24:25], v[156:157]
	v_pk_mul_f32 v[20:21], v[20:21], v[218:219]
	v_pk_mul_f32 v[30:31], v[30:31], v[146:147]
	v_pk_mul_f32 v[26:27], v[26:27], v[150:151]
	v_pk_mul_f32 v[22:23], v[22:23], v[154:155]
	v_pk_mul_f32 v[18:19], v[18:19], v[216:217]
